# scan compute loop: packed v_pk_mul_f32 of the state by exp(g_last) split into scalar v_mul_f32 pairs beside the MFMAs (bit-identical)
# speedup vs baseline: 1.0397x; 1.0070x over previous
; #define LAS __attribute__((address_space(3)))
; #define PACK8(v, base) pack8f((v)[(base) + 0], (v)[(base) + 1], (v)[(base) + 2], (v)[(base) + 3], (v)[(base) + 4], (v)[(base) + 5], (v)[(base) + 6], (v)[(base) + 7])
; #define SBAR() __builtin_amdgcn_sched_barrier(0)
; #define LOAD_WQ(f, g) do { _Pragma("unroll") for (int e = 0; e < 2; ++e) { f[4 * e] = LDF((2 * (g) + e) * 1024); f[4 * e + 1] = LDF((8 + 2 * (g) + e) * 1024); \
;                 f[4 * e + 2] = LDF(16384 + (2 * (g) + e) * 1024); f[4 * e + 3] = LDF(16384 + (8 + 2 * (g) + e) * 1024); } } while (0)
; #define COMP_WQ(f, g) do { _Pragma("unroll") for (int e = 0; e < 2; ++e) { const bf16x8 sb = PACK8(S[(2 * (g) + e) >> 1], ((2 * (g) + e) & 1) * 8); \
;                 vn[0] = MFMA32(f[4 * e], sb, vn[0]); vn[1] = MFMA32(f[4 * e + 1], sb, vn[1]); o[0] = MFMA32(f[4 * e + 2], sb, o[0]); o[1] = MFMA32(f[4 * e + 3], sb, o[1]); } } while (0)
; DI void gdn_scan(const Args& a, int l, int bh, LAS unsigned char* lds, const int tidx, const bool nostore) {
;     ...
;             const LAS unsigned char* buf = lds + (n & 1) * REC_BYTES + lane * 16;
;             bf16x8 fa[8], fb[8];
;     ...
;             LOAD_WQ(fa, 0); SBAR(); LOAD_WQ(fb, 1); SBAR();
;             COMP_WQ(fa, 0); SBAR(); LOAD_WQ(fa, 2); SBAR();
;             COMP_WQ(fb, 1); SBAR(); LOAD_WQ(fb, 3); SBAR();
;             COMP_WQ(fa, 2); SBAR();
; #pragma unroll
;             for (int e = 0; e < 8; ++e) fa[e] = LDF(49152 + e * 1024);
;             SBAR();
;             COMP_WQ(fb, 3); SBAR();
; #pragma unroll
;             for (int e = 0; e < 8; ++e) fb[e] = LDF(32768 + e * 1024);
;             SBAR();
;             bf16x8 Vb[4];
; #pragma unroll
;             for (int s2 = 0; s2 < 4; ++s2) Vb[s2] = PACK8(vn[s2 >> 1], (s2 & 1) * 8);
.Lscan_top_done:
	s_and_b32 s5, s4, 1
	s_mul_i32 s6, s5, 0xe000
	v_add_u32_e32 v204, s6, v150
	ds_read_b128 v[152:155], v204
	ds_read_b128 v[156:159], v204 offset:8192
	ds_read_b128 v[64:67], v204 offset:16384
	ds_read_b128 v[68:71], v204 offset:24576
	ds_read_b128 v[160:163], v204 offset:1024
	ds_read_b128 v[164:167], v204 offset:9216
	ds_read_b128 v[168:171], v204 offset:17408
	ds_read_b128 v[172:175], v204 offset:25600
	ds_read_b128 v[176:179], v204 offset:2048
	ds_read_b128 v[180:183], v204 offset:3072
	ds_read_b128 v[184:187], v204 offset:10240
	ds_read_b128 v[188:191], v204 offset:11264
	ds_read_b128 v[192:195], v204 offset:18432
	ds_read_b128 v[196:199], v204 offset:19456
	ds_read_b128 v[200:203], v204 offset:26624
	ds_read_b128 v[222:225], v204 offset:27648
	v_cvt_pk_bf16_f32 v226, v48, v49
	v_cvt_pk_bf16_f32 v227, v50, v51
	v_cvt_pk_bf16_f32 v228, v52, v53
	v_cvt_pk_bf16_f32 v229, v54, v55
	v_cvt_pk_bf16_f32 v230, v56, v57
	v_cvt_pk_bf16_f32 v231, v58, v59
	s_waitcnt lgkmcnt(13)
	v_mfma_f32_32x32x16_bf16 v[80:95], v[64:67], v[226:229], 0
	v_cvt_pk_bf16_f32 v232, v60, v61
	v_cvt_pk_bf16_f32 v233, v62, v63
	s_waitcnt lgkmcnt(12)
	v_mfma_f32_32x32x16_bf16 v[64:79], v[68:71], v[226:229], 0
	s_waitcnt lgkmcnt(9)
	v_mfma_f32_32x32x16_bf16 v[80:95], v[168:171], v[230:233], v[80:95]
	s_waitcnt lgkmcnt(8)
	v_mfma_f32_32x32x16_bf16 v[64:79], v[172:175], v[230:233], v[64:79]
	v_mfma_f32_32x32x16_bf16 v[112:127], v[152:155], v[226:229], v[112:127]
	v_mfma_f32_32x32x16_bf16 v[96:111], v[156:159], v[226:229], v[96:111]
	v_mfma_f32_32x32x16_bf16 v[112:127], v[160:163], v[230:233], v[112:127]
	ds_read_b128 v[152:155], v204 offset:4096
	ds_read_b128 v[156:159], v204 offset:5120
	ds_read_b128 v[160:163], v204 offset:12288
	ds_read_b128 v[168:171], v204 offset:13312
	ds_read_b128 v[172:175], v204 offset:20480
	ds_read_b128 v[226:229], v204 offset:21504
	ds_read_b128 v[234:237], v204 offset:28672
	ds_read_b128 v[248:251], v204 offset:29696
	v_mfma_f32_32x32x16_bf16 v[96:111], v[164:167], v[230:233], v[96:111]
	v_cvt_pk_bf16_f32 v164, v32, v33
	v_cvt_pk_bf16_f32 v165, v34, v35
	v_cvt_pk_bf16_f32 v166, v36, v37
	v_cvt_pk_bf16_f32 v167, v38, v39
	s_waitcnt lgkmcnt(11)
	s_nop 0
	v_mfma_f32_32x32x16_bf16 v[80:95], v[192:195], v[164:167], v[80:95]
	v_cvt_pk_bf16_f32 v192, v40, v41
	v_cvt_pk_bf16_f32 v193, v42, v43
	v_cvt_pk_bf16_f32 v194, v44, v45
	v_cvt_pk_bf16_f32 v195, v46, v47
	s_waitcnt lgkmcnt(9)
	v_mfma_f32_32x32x16_bf16 v[64:79], v[200:203], v[164:167], v[64:79]
	v_mfma_f32_32x32x16_bf16 v[80:95], v[196:199], v[192:195], v[80:95]
	s_waitcnt lgkmcnt(8)
	v_mfma_f32_32x32x16_bf16 v[64:79], v[222:225], v[192:195], v[64:79]
	v_mfma_f32_32x32x16_bf16 v[112:127], v[176:179], v[164:167], v[112:127]
	v_mfma_f32_32x32x16_bf16 v[96:111], v[184:187], v[164:167], v[96:111]
	v_mfma_f32_32x32x16_bf16 v[112:127], v[180:183], v[192:195], v[112:127]
	ds_read_b128 v[164:167], v204 offset:6144
	ds_read_b128 v[176:179], v204 offset:7168
	ds_read_b128 v[180:183], v204 offset:14336
	ds_read_b128 v[184:187], v204 offset:15360
	ds_read_b128 v[196:199], v204 offset:22528
	ds_read_b128 v[200:203], v204 offset:23552
	ds_read_b128 v[222:225], v204 offset:30720
	ds_read_b128 v[230:233], v204 offset:31744
	v_mfma_f32_32x32x16_bf16 v[96:111], v[188:191], v[192:195], v[96:111]
	v_cvt_pk_bf16_f32 v188, v16, v17
	v_cvt_pk_bf16_f32 v189, v18, v19
	v_cvt_pk_bf16_f32 v190, v20, v21
	v_cvt_pk_bf16_f32 v191, v22, v23
	s_waitcnt lgkmcnt(11)
	s_nop 0
	v_mfma_f32_32x32x16_bf16 v[80:95], v[172:175], v[188:191], v[80:95]
	v_cvt_pk_bf16_f32 v172, v24, v25
	v_cvt_pk_bf16_f32 v173, v26, v27
	v_cvt_pk_bf16_f32 v174, v28, v29
	v_cvt_pk_bf16_f32 v175, v30, v31
	s_waitcnt lgkmcnt(9)
	v_mfma_f32_32x32x16_bf16 v[64:79], v[234:237], v[188:191], v[64:79]
	v_mfma_f32_32x32x16_bf16 v[80:95], v[226:229], v[172:175], v[80:95]
	s_waitcnt lgkmcnt(8)
	v_mfma_f32_32x32x16_bf16 v[64:79], v[248:251], v[172:175], v[64:79]
	v_mfma_f32_32x32x16_bf16 v[112:127], v[152:155], v[188:191], v[112:127]
	v_mfma_f32_32x32x16_bf16 v[96:111], v[160:163], v[188:191], v[96:111]
	v_mfma_f32_32x32x16_bf16 v[112:127], v[156:159], v[172:175], v[112:127]
	ds_read_b128 v[152:155], v204 offset:49152
	ds_read_b128 v[156:159], v204 offset:50176
	ds_read_b128 v[160:163], v204 offset:51200
	ds_read_b128 v[188:191], v204 offset:52224
	ds_read_b128 v[192:195], v204 offset:53248
	ds_read_b128 v[226:229], v204 offset:54272
	ds_read_b128 v[234:237], v204 offset:55296
	ds_read_b128 v[248:251], v204 offset:56320
	v_mfma_f32_32x32x16_bf16 v[96:111], v[168:171], v[172:175], v[96:111]
	v_cvt_pk_bf16_f32 v168, v0, v1
	v_cvt_pk_bf16_f32 v169, v2, v3
	v_cvt_pk_bf16_f32 v170, v4, v5
	v_cvt_pk_bf16_f32 v171, v6, v7
	v_cvt_pk_bf16_f32 v172, v8, v9
	v_cvt_pk_bf16_f32 v173, v10, v11
	s_waitcnt lgkmcnt(13)
	v_mfma_f32_32x32x16_bf16 v[96:111], v[180:183], v[168:171], v[96:111]
	v_cvt_pk_bf16_f32 v174, v12, v13
	v_cvt_pk_bf16_f32 v175, v14, v15
	s_waitcnt lgkmcnt(11)
	v_mfma_f32_32x32x16_bf16 v[80:95], v[196:199], v[168:171], v[80:95]
	s_waitcnt lgkmcnt(9)
	v_mfma_f32_32x32x16_bf16 v[64:79], v[222:225], v[168:171], v[64:79]
	v_mfma_f32_32x32x16_bf16 v[96:111], v[184:187], v[172:175], v[96:111]
	v_mfma_f32_32x32x16_bf16 v[80:95], v[200:203], v[172:175], v[80:95]
	s_waitcnt lgkmcnt(8)
; #define MFMA32(a, b, c) __builtin_amdgcn_mfma_f32_32x32x16_bf16((a), (b), (c), 0, 0, 0)
; #define PACK8(v, base) pack8f((v)[(base) + 0], (v)[(base) + 1], (v)[(base) + 2], (v)[(base) + 3], (v)[(base) + 4], (v)[(base) + 5], (v)[(base) + 6], (v)[(base) + 7])
; #define SBAR() __builtin_amdgcn_sched_barrier(0)
; DI void gdn_scan(const Args& a, int l, int bh, LAS unsigned char* lds, const int tidx, const bool nostore) {
;     ...
;             bf16x8 Vb[4];
; #pragma unroll
;             for (int s2 = 0; s2 < 4; ++s2) Vb[s2] = PACK8(vn[s2 >> 1], (s2 & 1) * 8);
; #pragma unroll
;             for (int s2 = 0; s2 < 4; ++s2)
; #pragma unroll
;                 for (int mt = 0; mt < 2; ++mt) o[mt] = MFMA32(fa[mt * 4 + s2], Vb[s2], o[mt]);
;             SBAR();
; #pragma unroll
;             for (int e = 0; e < 8; ++e) fa[e] = LDF(32768 + 8192 + e * 1024);
;             SBAR();
; #pragma unroll
;             for (int t = 0; t < 4; ++t)
; #pragma unroll
;                 for (int r = 0; r < 16; ++r) S[t][r] *= eg;
; #pragma unroll
;             for (int s2 = 0; s2 < 4; ++s2)
; #pragma unroll
;                 for (int t = 0; t < 2; ++t) S[t] = MFMA32(fb[t * 4 + s2], Vb[s2], S[t]);
;             SBAR();
; #pragma unroll
;             for (int s2 = 0; s2 < 4; ++s2)
; #pragma unroll
;                 for (int t = 2; t < 4; ++t) S[t] = MFMA32(fa[(t - 2) * 4 + s2], Vb[s2], S[t]);
	v_mfma_f32_32x32x16_bf16 v[64:79], v[230:233], v[172:175], v[64:79]
	v_mfma_f32_32x32x16_bf16 v[112:127], v[164:167], v[168:171], v[112:127]
	ds_read_b128 v[164:167], v204 offset:32768
	ds_read_b128 v[168:171], v204 offset:33792
	ds_read_b128 v[180:183], v204 offset:34816
	ds_read_b128 v[184:187], v204 offset:35840
	ds_read_b128 v[196:199], v204 offset:36864
	ds_read_b128 v[200:203], v204 offset:37888
	ds_read_b128 v[222:225], v204 offset:38912
	ds_read_b128 v[230:233], v204 offset:39936
	v_mfma_f32_32x32x16_bf16 v[112:127], v[176:179], v[172:175], v[112:127]
	s_nop 11
	v_cvt_pk_bf16_f32 v112, v112, v113
	v_cvt_pk_bf16_f32 v113, v114, v115
	v_cvt_pk_bf16_f32 v114, v116, v117
	v_cvt_pk_bf16_f32 v115, v118, v119
	v_cvt_pk_bf16_f32 v116, v120, v121
	v_cvt_pk_bf16_f32 v117, v122, v123
	s_waitcnt lgkmcnt(14)
	v_mfma_f32_32x32x16_bf16 v[80:95], v[152:155], v[112:115], v[80:95]
	v_cvt_pk_bf16_f32 v118, v124, v125
	v_cvt_pk_bf16_f32 v119, v126, v127
	v_cvt_pk_bf16_f32 v96, v96, v97
	v_cvt_pk_bf16_f32 v97, v98, v99
	v_cvt_pk_bf16_f32 v98, v100, v101
	v_cvt_pk_bf16_f32 v99, v102, v103
	v_cvt_pk_bf16_f32 v100, v104, v105
	s_waitcnt lgkmcnt(11)
	v_mfma_f32_32x32x16_bf16 v[64:79], v[192:195], v[112:115], v[64:79]
	v_cvt_pk_bf16_f32 v101, v106, v107
	v_cvt_pk_bf16_f32 v102, v108, v109
	v_cvt_pk_bf16_f32 v103, v110, v111
	v_mfma_f32_32x32x16_bf16 v[80:95], v[156:159], v[116:119], v[80:95]
	s_waitcnt lgkmcnt(10)
	v_mfma_f32_32x32x16_bf16 v[64:79], v[226:229], v[116:119], v[64:79]
	v_mfma_f32_32x32x16_bf16 v[80:95], v[160:163], v[96:99], v[80:95]
	s_waitcnt lgkmcnt(9)
	v_mfma_f32_32x32x16_bf16 v[64:79], v[234:237], v[96:99], v[64:79]
	v_mfma_f32_32x32x16_bf16 v[80:95], v[188:191], v[100:103], v[80:95]
	s_waitcnt lgkmcnt(8)
	v_mfma_f32_32x32x16_bf16 v[64:79], v[248:251], v[100:103], v[64:79]
	ds_read_b128 v[104:107], v204 offset:40960
	ds_read_b128 v[108:111], v204 offset:41984
	ds_read_b128 v[120:123], v204 offset:43008
	ds_read_b128 v[124:127], v204 offset:44032
	ds_read_b128 v[152:155], v204 offset:45056
	ds_read_b128 v[156:159], v204 offset:46080
	ds_read_b128 v[160:163], v204 offset:47104
	ds_read_b128 v[172:175], v204 offset:48128
	s_nop 0
	v_mul_f32_e32 v62, v148, v62
	v_mul_f32_e32 v63, v148, v63
	v_mul_f32_e32 v60, v148, v60
	v_mul_f32_e32 v61, v148, v61
	v_mul_f32_e32 v58, v148, v58
	v_mul_f32_e32 v59, v148, v59
	v_mul_f32_e32 v56, v148, v56
	v_mul_f32_e32 v57, v148, v57
	v_mul_f32_e32 v54, v148, v54
	v_mul_f32_e32 v55, v148, v55
	v_mul_f32_e32 v52, v148, v52
	v_mul_f32_e32 v53, v148, v53
	v_mul_f32_e32 v50, v148, v50
	v_mul_f32_e32 v51, v148, v51
	v_mul_f32_e32 v48, v148, v48
	v_mul_f32_e32 v49, v148, v49
	v_mul_f32_e32 v46, v148, v46
	v_mul_f32_e32 v47, v148, v47
	v_mul_f32_e32 v44, v148, v44
	v_mul_f32_e32 v45, v148, v45
	v_mul_f32_e32 v42, v148, v42
	v_mul_f32_e32 v43, v148, v43
	v_mul_f32_e32 v40, v148, v40
	v_mul_f32_e32 v41, v148, v41
	v_mul_f32_e32 v38, v148, v38
	v_mul_f32_e32 v39, v148, v39
	v_mul_f32_e32 v36, v148, v36
	v_mul_f32_e32 v37, v148, v37
	v_mul_f32_e32 v34, v148, v34
	v_mul_f32_e32 v35, v148, v35
	v_mul_f32_e32 v32, v148, v32
	v_mul_f32_e32 v33, v148, v33
	s_waitcnt lgkmcnt(14)
	v_mfma_f32_32x32x16_bf16 v[48:63], v[164:167], v[112:115], v[48:63]
	v_mul_f32_e64 v30, v30, v148
	v_mul_f32_e64 v31, v31, v148
	v_mul_f32_e64 v28, v28, v148
	v_mul_f32_e64 v29, v29, v148
	v_mul_f32_e64 v26, v26, v148
	v_mul_f32_e64 v27, v27, v148
	v_mul_f32_e32 v24, v148, v24
	v_mul_f32_e32 v25, v148, v25
	v_mul_f32_e32 v22, v148, v22
	v_mul_f32_e32 v23, v148, v23
	v_mul_f32_e32 v20, v148, v20
	v_mul_f32_e32 v21, v148, v21
	v_mul_f32_e32 v18, v148, v18
	v_mul_f32_e32 v19, v148, v19
	s_waitcnt lgkmcnt(11)
	v_mfma_f32_32x32x16_bf16 v[32:47], v[196:199], v[112:115], v[32:47]
	v_mul_f32_e64 v16, v16, v148
	v_mul_f32_e64 v17, v17, v148
	v_mul_f32_e64 v14, v14, v148
	v_mul_f32_e64 v15, v15, v148
	v_mul_f32_e64 v12, v12, v148
	v_mul_f32_e64 v13, v13, v148
	v_mul_f32_e32 v10, v148, v10
	v_mul_f32_e32 v11, v148, v11
	v_mul_f32_e32 v8, v148, v8
	v_mul_f32_e32 v9, v148, v9
	v_mul_f32_e32 v6, v148, v6
	v_mul_f32_e32 v7, v148, v7
	v_mul_f32_e32 v4, v148, v4
	v_mul_f32_e32 v5, v148, v5
	v_mfma_f32_32x32x16_bf16 v[48:63], v[168:171], v[116:119], v[48:63]
	v_mul_f32_e64 v2, v2, v148
	v_mul_f32_e64 v3, v3, v148
	v_mul_f32_e64 v0, v0, v148
	v_mul_f32_e64 v1, v1, v148
	s_waitcnt lgkmcnt(10)
	v_mfma_f32_32x32x16_bf16 v[32:47], v[200:203], v[116:119], v[32:47]
	v_mfma_f32_32x32x16_bf16 v[48:63], v[180:183], v[96:99], v[48:63]
	s_waitcnt lgkmcnt(9)
	v_mfma_f32_32x32x16_bf16 v[32:47], v[222:225], v[96:99], v[32:47]
	v_mfma_f32_32x32x16_bf16 v[48:63], v[184:187], v[100:103], v[48:63]
	s_waitcnt lgkmcnt(8)
	v_mfma_f32_32x32x16_bf16 v[32:47], v[230:233], v[100:103], v[32:47]
	s_waitcnt lgkmcnt(7)
	v_mfma_f32_32x32x16_bf16 v[16:31], v[104:107], v[112:115], v[16:31]
	s_mulk_i32 s5, 0x4400
	v_cvt_pk_bf16_f32 v80, v80, v81
	v_cvt_pk_bf16_f32 v81, v82, v83
	v_cvt_pk_bf16_f32 v64, v64, v65
	v_cvt_pk_bf16_f32 v65, v66, v67
	s_add_i32 s4, s4, 1
	s_add_u32 s0, s0, 4
	s_waitcnt lgkmcnt(3)
	v_mfma_f32_32x32x16_bf16 v[0:15], v[152:155], v[112:115], v[0:15]
	s_addc_u32 s1, s1, 0
	v_lshl_add_u64 v[144:145], v[144:145], 0, s[10:11]
	v_lshl_add_u64 v[146:147], v[146:147], 0, s[10:11]
	s_cmp_eq_u32 s4, 63
	s_nop 0
	s_nop 0
	v_mfma_f32_32x32x16_bf16 v[16:31], v[108:111], v[116:119], v[16:31]
	s_waitcnt lgkmcnt(2)
	v_mfma_f32_32x32x16_bf16 v[0:15], v[156:159], v[116:119], v[0:15]
	v_mfma_f32_32x32x16_bf16 v[16:31], v[120:123], v[96:99], v[16:31]
	s_waitcnt lgkmcnt(1)
; #define LAS __attribute__((address_space(3)))
; DI unsigned pk2(float lo, float hi) { const f32x2_t v = {lo, hi}; return __builtin_bit_cast(unsigned, __builtin_convertvector(v, bf16x2_t)); }
; DI void gdn_scan(const Args& a, int l, int bh, LAS unsigned char* lds, const int tidx, const bool nostore) {
;     ...
;             for (int mt = 0; mt < 2; ++mt) {
; #pragma unroll
;                 for (int g8 = 0; g8 < 2; ++g8) { const u32x4 u = un[mt][g8];
;                     vn[mt][8 * g8] = bflo(u.x); vn[mt][8 * g8 + 1] = bfhi(u.x); vn[mt][8 * g8 + 2] = bflo(u.y); vn[mt][8 * g8 + 3] = bfhi(u.y);
;                     vn[mt][8 * g8 + 4] = bflo(u.z); vn[mt][8 * g8 + 5] = bfhi(u.z); vn[mt][8 * g8 + 6] = bflo(u.w); vn[mt][8 * g8 + 7] = bfhi(u.w); }
; #pragma unroll
;                 for (int r = 0; r < 16; ++r) o[mt][r] = 0.f; }
;             if (n < 63) {
; #pragma unroll
;                 for (int mt = 0; mt < 2; ++mt) { const u32x4* up = (const u32x4*)(urec + (size_t)(n + 1) * 16384) + ((size_t)((wave * 2 + mt) * 64 + lane)) * 2; un[mt][0] = up[0]; un[mt][1] = up[1]; }
;                 egn = egl[n + 1];
;             }
;             const LAS unsigned char* buf = lds + (n & 1) * REC_BYTES + lane * 16;
;             bf16x8 fa[8], fb[8];
;     ...
;             LOAD_WQ(fa, 0); SBAR(); LOAD_WQ(fb, 1); SBAR();
;             COMP_WQ(fa, 0); SBAR(); LOAD_WQ(fa, 2); SBAR();
;     ...
;             for (int s2 = 0; s2 < 4; ++s2)
; #pragma unroll
;                 for (int t = 0; t < 2; ++t) S[t] = MFMA32(fb[t * 4 + s2], Vb[s2], S[t]);
;             SBAR();
; #pragma unroll
;             for (int s2 = 0; s2 < 4; ++s2)
; #pragma unroll
;                 for (int t = 2; t < 4; ++t) S[t] = MFMA32(fa[(t - 2) * 4 + s2], Vb[s2], S[t]);
;     ...
;             LAS bf16_t* ost = (LAS bf16_t*)(lds + SCAN_OST + (n & 1) * OST_BYTES) + (4 * hf) * OST_PITCH + wave * 32 + (lane & 31);
; #pragma unroll
;             for (int mt = 0; mt < 2; ++mt)
; #pragma unroll
;                 for (int i = 0; i < 4; ++i) { const unsigned w0 = pk2(o[mt][4 * i], o[mt][4 * i + 1]), w1 = pk2(o[mt][4 * i + 2], o[mt][4 * i + 3]);
;                     LAS bf16_t* d = ost + (mt * 32 + 8 * i) * OST_PITCH;
;                     d[0] = (bf16_t)(w0 & 0xffffu); d[OST_PITCH] = (bf16_t)(w0 >> 16); d[2 * OST_PITCH] = (bf16_t)(w1 & 0xffffu); d[3 * OST_PITCH] = (bf16_t)(w1 >> 16); }
;             LDSBAR();
	v_mfma_f32_32x32x16_bf16 v[0:15], v[160:163], v[96:99], v[0:15]
	v_add_u32_e32 v96, s5, v149
	ds_write_b16 v96, v80
	ds_write_b16_d16_hi v96, v80 offset:272
	ds_write_b16 v96, v81 offset:544
	ds_write_b16_d16_hi v96, v81 offset:816
	v_cvt_pk_bf16_f32 v80, v84, v85
	v_cvt_pk_bf16_f32 v81, v86, v87
	ds_write_b16 v96, v80 offset:2176
	ds_write_b16_d16_hi v96, v80 offset:2448
	ds_write_b16 v96, v81 offset:2720
	ds_write_b16_d16_hi v96, v81 offset:2992
	v_cvt_pk_bf16_f32 v80, v88, v89
	v_cvt_pk_bf16_f32 v81, v90, v91
	v_mfma_f32_32x32x16_bf16 v[16:31], v[124:127], v[100:103], v[16:31]
	ds_write_b16 v96, v80 offset:4352
	ds_write_b16_d16_hi v96, v80 offset:4624
	ds_write_b16 v96, v81 offset:4896
	ds_write_b16_d16_hi v96, v81 offset:5168
	v_cvt_pk_bf16_f32 v80, v92, v93
	v_cvt_pk_bf16_f32 v81, v94, v95
	ds_write_b16 v96, v80 offset:6528
	ds_write_b16_d16_hi v96, v80 offset:6800
	ds_write_b16 v96, v81 offset:7072
	ds_write_b16_d16_hi v96, v81 offset:7344
	ds_write_b16 v96, v64 offset:8704
	ds_write_b16_d16_hi v96, v64 offset:8976
	ds_write_b16 v96, v65 offset:9248
	ds_write_b16_d16_hi v96, v65 offset:9520
	v_cvt_pk_bf16_f32 v64, v68, v69
	v_cvt_pk_bf16_f32 v65, v70, v71
	s_waitcnt lgkmcnt(14)
	v_mfma_f32_32x32x16_bf16 v[0:15], v[172:175], v[100:103], v[0:15]
	ds_write_b16 v96, v64 offset:10880
	ds_write_b16_d16_hi v96, v64 offset:11152
	ds_write_b16 v96, v65 offset:11424
	ds_write_b16_d16_hi v96, v65 offset:11696
	v_cvt_pk_bf16_f32 v64, v72, v73
	v_cvt_pk_bf16_f32 v65, v74, v75
	ds_write_b16 v96, v64 offset:13056
	ds_write_b16_d16_hi v96, v64 offset:13328
	ds_write_b16 v96, v65 offset:13600
	ds_write_b16_d16_hi v96, v65 offset:13872
	v_cvt_pk_bf16_f32 v64, v76, v77
	v_cvt_pk_bf16_f32 v65, v78, v79
	ds_write_b16 v96, v64 offset:15232
	ds_write_b16_d16_hi v96, v64 offset:15504
	ds_write_b16 v96, v65 offset:15776
	ds_write_b16_d16_hi v96, v65 offset:16048
	s_waitcnt lgkmcnt(0)
	s_barrier
	s_cbranch_scc0 .LBB0_380
	s_waitcnt vmcnt(5)
	v_add_u32_e32 v96, 0x10000, v150
	v_lshlrev_b32_e32 v80, 16, v132
	v_and_b32_e32 v81, 0xffff0000, v132
	v_lshlrev_b32_e32 v82, 16, v133
	v_and_b32_e32 v83, 0xffff0000, v133
	v_lshlrev_b32_e32 v84, 16, v134
	v_and_b32_e32 v85, 0xffff0000, v134
	v_lshlrev_b32_e32 v86, 16, v135
	v_and_b32_e32 v87, 0xffff0000, v135
	v_lshlrev_b32_e32 v88, 16, v128
	v_and_b32_e32 v89, 0xffff0000, v128
	v_lshlrev_b32_e32 v90, 16, v129
	v_and_b32_e32 v91, 0xffff0000, v129
	v_lshlrev_b32_e32 v92, 16, v130
	v_and_b32_e32 v93, 0xffff0000, v130
	v_lshlrev_b32_e32 v94, 16, v131
	v_and_b32_e32 v95, 0xffff0000, v131
	ds_read_b128 v[128:131], v150 offset:57344
	ds_read_b128 v[132:135], v96
	v_add_u32_e32 v96, 0x12000, v150
	v_add_u32_e32 v100, 0x14000, v150
	v_add_u32_e32 v104, 0x10400, v150
	v_and_b32_e32 v79, 0xffff0000, v139
	v_lshlrev_b32_e32 v64, 16, v140
	v_and_b32_e32 v65, 0xffff0000, v140
	v_lshlrev_b32_e32 v66, 16, v141
	v_and_b32_e32 v67, 0xffff0000, v141
	v_lshlrev_b32_e32 v68, 16, v142
	v_and_b32_e32 v69, 0xffff0000, v142
	v_lshlrev_b32_e32 v70, 16, v143
	v_and_b32_e32 v71, 0xffff0000, v143
	v_lshlrev_b32_e32 v72, 16, v136
	v_and_b32_e32 v73, 0xffff0000, v136
	v_lshlrev_b32_e32 v74, 16, v137
	v_and_b32_e32 v75, 0xffff0000, v137
	v_lshlrev_b32_e32 v76, 16, v138
	v_and_b32_e32 v77, 0xffff0000, v138
	v_lshlrev_b32_e32 v78, 16, v139
	ds_read_b128 v[96:99], v96
	ds_read_b128 v[100:103], v100
	ds_read_b128 v[136:139], v150 offset:58368
	ds_read_b128 v[140:143], v104
	v_add_u32_e32 v104, 0x12400, v150
	ds_read_b128 v[144:147], v104
	v_add_u32_e32 v104, 0x14400, v150
	ds_read_b128 v[152:155], v104
	v_add_u32_e32 v104, 0x10800, v150
	v_add_u32_e32 v105, 0x12800, v150
	ds_read_b128 v[156:159], v104
	ds_read_b128 v[160:163], v105
	v_add_u32_e32 v104, 0x14800, v150
	ds_read_b128 v[164:167], v150 offset:59392
	ds_read_b128 v[168:171], v150 offset:60416
	v_add_u32_e32 v105, 0x10c00, v150
	ds_read_b128 v[172:175], v104
	ds_read_b128 v[176:179], v105
	v_add_u32_e32 v104, 0x12c00, v150
	v_add_u32_e32 v105, 0x14c00, v150
	ds_read_b128 v[180:183], v104
	ds_read_b128 v[184:187], v105
	v_cvt_pk_bf16_f32 v48, v48, v49
	v_cvt_pk_bf16_f32 v49, v50, v51
	v_cvt_pk_bf16_f32 v50, v52, v53
	v_cvt_pk_bf16_f32 v51, v54, v55
	v_cvt_pk_bf16_f32 v52, v56, v57
	v_cvt_pk_bf16_f32 v53, v58, v59
	s_waitcnt lgkmcnt(13)
	v_mfma_f32_32x32x16_bf16 v[112:127], v[96:99], v[48:51], 0
	v_cvt_pk_bf16_f32 v54, v60, v61
	v_cvt_pk_bf16_f32 v55, v62, v63
	s_waitcnt lgkmcnt(12)
	v_mfma_f32_32x32x16_bf16 v[96:111], v[100:103], v[48:51], 0
	s_waitcnt lgkmcnt(9)
	v_mfma_f32_32x32x16_bf16 v[112:127], v[144:147], v[52:55], v[112:127]
	s_waitcnt lgkmcnt(8)
	v_mfma_f32_32x32x16_bf16 v[96:111], v[152:155], v[52:55], v[96:111]
	v_mfma_f32_32x32x16_bf16 v[80:95], v[128:131], v[48:51], v[80:95]
	v_add_u32_e32 v56, 0x13000, v150
	v_add_u32_e32 v144, 0x13400, v150
	v_add_u32_e32 v148, 0x15400, v150
	v_mfma_f32_32x32x16_bf16 v[64:79], v[132:135], v[48:51], v[64:79]
	v_add_u32_e32 v48, 0x11000, v150
	v_add_u32_e32 v132, 0x15000, v150
	ds_read_b128 v[48:51], v48
	ds_read_b128 v[56:59], v56
	ds_read_b128 v[60:63], v150 offset:61440
	ds_read_b128 v[128:131], v150 offset:62464
	v_mfma_f32_32x32x16_bf16 v[80:95], v[136:139], v[52:55], v[80:95]
	v_add_u32_e32 v136, 0x11400, v150
	ds_read_b128 v[132:135], v132
	ds_read_b128 v[136:139], v136
	ds_read_b128 v[144:147], v144
	ds_read_b128 v[152:155], v148
	v_mfma_f32_32x32x16_bf16 v[64:79], v[140:143], v[52:55], v[64:79]
	v_cvt_pk_bf16_f32 v32, v32, v33
	v_cvt_pk_bf16_f32 v33, v34, v35
	v_cvt_pk_bf16_f32 v34, v36, v37
	v_cvt_pk_bf16_f32 v35, v38, v39
	v_cvt_pk_bf16_f32 v36, v40, v41
	v_cvt_pk_bf16_f32 v37, v42, v43
	s_waitcnt lgkmcnt(14)
; #define LAS __attribute__((address_space(3)))
; #define MFMA32(a, b, c) __builtin_amdgcn_mfma_f32_32x32x16_bf16((a), (b), (c), 0, 0, 0)
; DI void gdn_scan(const Args& a, int l, int bh, LAS unsigned char* lds, const int tidx, const bool nostore) {
;     ...
;             LOAD_WQ(fa, 0); SBAR(); LOAD_WQ(fb, 1); SBAR();
;             COMP_WQ(fa, 0); SBAR(); LOAD_WQ(fa, 2); SBAR();
;             COMP_WQ(fb, 1); SBAR(); LOAD_WQ(fb, 3); SBAR();
;             COMP_WQ(fa, 2); SBAR();
; #pragma unroll
;             for (int e = 0; e < 8; ++e) fa[e] = LDF(49152 + e * 1024);
;             SBAR();
;             COMP_WQ(fb, 3); SBAR();
; #pragma unroll
;             for (int e = 0; e < 8; ++e) fb[e] = LDF(32768 + e * 1024);
;             SBAR();
;             bf16x8 Vb[4];
; #pragma unroll
;             for (int s2 = 0; s2 < 4; ++s2) Vb[s2] = PACK8(vn[s2 >> 1], (s2 & 1) * 8);
; #pragma unroll
;             for (int s2 = 0; s2 < 4; ++s2)
; #pragma unroll
;                 for (int mt = 0; mt < 2; ++mt) o[mt] = MFMA32(fa[mt * 4 + s2], Vb[s2], o[mt]);
;             SBAR();
; #pragma unroll
;             for (int e = 0; e < 8; ++e) fa[e] = LDF(32768 + 8192 + e * 1024);
;             SBAR();
; #pragma unroll
;             for (int t = 0; t < 4; ++t)
; #pragma unroll
;                 for (int r = 0; r < 16; ++r) S[t][r] *= eg;
; #pragma unroll
;             for (int s2 = 0; s2 < 4; ++s2)
; #pragma unroll
;                 for (int t = 0; t < 2; ++t) S[t] = MFMA32(fb[t * 4 + s2], Vb[s2], S[t]);
;             SBAR();
; #pragma unroll
;             for (int s2 = 0; s2 < 4; ++s2)
; #pragma unroll
;                 for (int t = 2; t < 4; ++t) S[t] = MFMA32(fa[(t - 2) * 4 + s2], Vb[s2], S[t]);
;     ...
;             LAS bf16_t* ost = (LAS bf16_t*)(lds + SCAN_OST + (n & 1) * OST_BYTES) + (4 * hf) * OST_PITCH + wave * 32 + (lane & 31);
; #pragma unroll
;             for (int mt = 0; mt < 2; ++mt)
; #pragma unroll
;                 for (int i = 0; i < 4; ++i) { const unsigned w0 = pk2(o[mt][4 * i], o[mt][4 * i + 1]), w1 = pk2(o[mt][4 * i + 2], o[mt][4 * i + 3]);
;                     LAS bf16_t* d = ost + (mt * 32 + 8 * i) * OST_PITCH;
;                     d[0] = (bf16_t)(w0 & 0xffffu); d[OST_PITCH] = (bf16_t)(w0 >> 16); d[2 * OST_PITCH] = (bf16_t)(w1 & 0xffffu); d[3 * OST_PITCH] = (bf16_t)(w1 >> 16); }
;             LDSBAR();
;         }
;         __builtin_amdgcn_s_setprio(0);
	v_mfma_f32_32x32x16_bf16 v[112:127], v[160:163], v[32:35], v[112:127]
	v_cvt_pk_bf16_f32 v38, v44, v45
	v_cvt_pk_bf16_f32 v39, v46, v47
	s_waitcnt lgkmcnt(11)
	v_mfma_f32_32x32x16_bf16 v[96:111], v[172:175], v[32:35], v[96:111]
	s_waitcnt lgkmcnt(9)
	v_mfma_f32_32x32x16_bf16 v[112:127], v[180:183], v[36:39], v[112:127]
	s_waitcnt lgkmcnt(8)
	v_mfma_f32_32x32x16_bf16 v[96:111], v[184:187], v[36:39], v[96:111]
	v_mfma_f32_32x32x16_bf16 v[80:95], v[164:167], v[32:35], v[80:95]
	v_add_u32_e32 v40, 0x13800, v150
	v_add_u32_e32 v140, 0x15800, v150
	v_add_u32_e32 v148, 0x11c00, v150
	v_add_u32_e32 v151, 0x15c00, v150
	v_mfma_f32_32x32x16_bf16 v[64:79], v[156:159], v[32:35], v[64:79]
	v_add_u32_e32 v32, 0x11800, v150
	ds_read_b128 v[32:35], v32
	ds_read_b128 v[40:43], v40
	ds_read_b128 v[44:47], v150 offset:63488
	ds_read_b128 v[52:55], v150 offset:64512
	ds_read_b128 v[140:143], v140
	ds_read_b128 v[156:159], v148
	v_add_u32_e32 v148, 0x13c00, v150
	ds_read_b128 v[160:163], v148
	ds_read_b128 v[164:167], v151
	v_mfma_f32_32x32x16_bf16 v[80:95], v[168:171], v[36:39], v[80:95]
	v_mfma_f32_32x32x16_bf16 v[64:79], v[176:179], v[36:39], v[64:79]
	v_cvt_pk_bf16_f32 v16, v16, v17
	v_cvt_pk_bf16_f32 v17, v18, v19
	v_cvt_pk_bf16_f32 v18, v20, v21
	v_cvt_pk_bf16_f32 v19, v22, v23
	v_cvt_pk_bf16_f32 v20, v24, v25
	v_cvt_pk_bf16_f32 v21, v26, v27
	s_waitcnt lgkmcnt(14)
	v_mfma_f32_32x32x16_bf16 v[112:127], v[56:59], v[16:19], v[112:127]
	v_cvt_pk_bf16_f32 v22, v28, v29
	v_cvt_pk_bf16_f32 v23, v30, v31
	s_waitcnt lgkmcnt(11)
	v_mfma_f32_32x32x16_bf16 v[96:111], v[132:135], v[16:19], v[96:111]
	s_waitcnt lgkmcnt(9)
	v_mfma_f32_32x32x16_bf16 v[112:127], v[144:147], v[20:23], v[112:127]
	s_waitcnt lgkmcnt(8)
	v_mfma_f32_32x32x16_bf16 v[96:111], v[152:155], v[20:23], v[96:111]
	v_mfma_f32_32x32x16_bf16 v[80:95], v[60:63], v[16:19], v[80:95]
	v_add_u32_e32 v24, 0x1a000, v150
	v_add_u32_e32 v25, 0x1a400, v150
	v_add_u32_e32 v28, 0x1a800, v150
	v_add_u32_e32 v36, 0x1ac00, v150
	v_add_u32_e32 v56, 0x1b400, v150
	v_add_u32_e32 v60, 0x1b800, v150
	v_mfma_f32_32x32x16_bf16 v[64:79], v[48:51], v[16:19], v[64:79]
	v_add_u32_e32 v48, 0x1b000, v150
	ds_read_b128 v[16:19], v24
	ds_read_b128 v[24:27], v25
	ds_read_b128 v[28:31], v28
	ds_read_b128 v[36:39], v36
	ds_read_b128 v[48:51], v48
	ds_read_b128 v[56:59], v56
	v_mfma_f32_32x32x16_bf16 v[80:95], v[128:131], v[20:23], v[80:95]
	v_add_u32_e32 v128, 0x1bc00, v150
	ds_read_b128 v[60:63], v60
	ds_read_b128 v[128:131], v128
	v_mfma_f32_32x32x16_bf16 v[64:79], v[136:139], v[20:23], v[64:79]
	v_cvt_pk_bf16_f32 v0, v0, v1
	v_cvt_pk_bf16_f32 v1, v2, v3
	v_cvt_pk_bf16_f32 v2, v4, v5
	v_cvt_pk_bf16_f32 v3, v6, v7
	v_cvt_pk_bf16_f32 v4, v8, v9
	v_cvt_pk_bf16_f32 v5, v10, v11
	s_waitcnt lgkmcnt(14)
	v_mfma_f32_32x32x16_bf16 v[64:79], v[32:35], v[0:3], v[64:79]
	v_cvt_pk_bf16_f32 v6, v12, v13
	v_cvt_pk_bf16_f32 v7, v14, v15
	v_mfma_f32_32x32x16_bf16 v[112:127], v[40:43], v[0:3], v[112:127]
	s_waitcnt lgkmcnt(11)
	v_mfma_f32_32x32x16_bf16 v[96:111], v[140:143], v[0:3], v[96:111]
	s_waitcnt lgkmcnt(10)
	v_mfma_f32_32x32x16_bf16 v[64:79], v[156:159], v[4:7], v[64:79]
	s_waitcnt lgkmcnt(9)
	v_mfma_f32_32x32x16_bf16 v[112:127], v[160:163], v[4:7], v[112:127]
	s_waitcnt lgkmcnt(8)
	v_mfma_f32_32x32x16_bf16 v[96:111], v[164:167], v[4:7], v[96:111]
	v_mfma_f32_32x32x16_bf16 v[80:95], v[44:47], v[0:3], v[80:95]
	v_mfma_f32_32x32x16_bf16 v[80:95], v[52:55], v[4:7], v[80:95]
	s_nop 11
	v_cvt_pk_bf16_f32 v0, v80, v81
	v_cvt_pk_bf16_f32 v1, v82, v83
	v_cvt_pk_bf16_f32 v2, v84, v85
	v_cvt_pk_bf16_f32 v3, v86, v87
	s_waitcnt lgkmcnt(7)
	s_nop 0
	v_mfma_f32_32x32x16_bf16 v[112:127], v[16:19], v[0:3], v[112:127]
	s_waitcnt lgkmcnt(3)
	v_mfma_f32_32x32x16_bf16 v[96:111], v[48:51], v[0:3], v[96:111]
	v_cvt_pk_bf16_f32 v0, v88, v89
	v_cvt_pk_bf16_f32 v1, v90, v91
	v_cvt_pk_bf16_f32 v2, v92, v93
	v_cvt_pk_bf16_f32 v3, v94, v95
	s_nop 1
	v_mfma_f32_32x32x16_bf16 v[112:127], v[24:27], v[0:3], v[112:127]
	s_waitcnt lgkmcnt(2)
	v_mfma_f32_32x32x16_bf16 v[96:111], v[56:59], v[0:3], v[96:111]
	v_cvt_pk_bf16_f32 v0, v64, v65
	v_cvt_pk_bf16_f32 v1, v66, v67
	v_cvt_pk_bf16_f32 v2, v68, v69
	v_cvt_pk_bf16_f32 v3, v70, v71
	s_nop 1
	v_mfma_f32_32x32x16_bf16 v[112:127], v[28:31], v[0:3], v[112:127]
	s_waitcnt lgkmcnt(1)
	v_mfma_f32_32x32x16_bf16 v[96:111], v[60:63], v[0:3], v[96:111]
	v_cvt_pk_bf16_f32 v0, v72, v73
	v_cvt_pk_bf16_f32 v1, v74, v75
	v_cvt_pk_bf16_f32 v2, v76, v77
	v_cvt_pk_bf16_f32 v3, v78, v79
	s_nop 1
	v_mfma_f32_32x32x16_bf16 v[112:127], v[36:39], v[0:3], v[112:127]
	s_waitcnt lgkmcnt(0)
	v_mfma_f32_32x32x16_bf16 v[96:111], v[128:131], v[0:3], v[96:111]
	s_nop 9
	v_cvt_pk_bf16_f32 v0, v112, v113
	v_cvt_pk_bf16_f32 v1, v114, v115
	ds_write_b16 v149, v0 offset:17408
	ds_write_b16_d16_hi v149, v0 offset:17680
	ds_write_b16 v149, v1 offset:17952
	ds_write_b16_d16_hi v149, v1 offset:18224
	v_cvt_pk_bf16_f32 v0, v116, v117
	v_cvt_pk_bf16_f32 v1, v118, v119
	ds_write_b16 v149, v0 offset:19584
	ds_write_b16_d16_hi v149, v0 offset:19856
	ds_write_b16 v149, v1 offset:20128
	ds_write_b16_d16_hi v149, v1 offset:20400
	v_cvt_pk_bf16_f32 v0, v120, v121
	v_cvt_pk_bf16_f32 v1, v122, v123
	ds_write_b16 v149, v0 offset:21760
	ds_write_b16_d16_hi v149, v0 offset:22032
	ds_write_b16 v149, v1 offset:22304
	ds_write_b16_d16_hi v149, v1 offset:22576
	v_cvt_pk_bf16_f32 v0, v124, v125
	v_cvt_pk_bf16_f32 v1, v126, v127
	ds_write_b16 v149, v0 offset:23936
	ds_write_b16_d16_hi v149, v0 offset:24208
	ds_write_b16 v149, v1 offset:24480
	ds_write_b16_d16_hi v149, v1 offset:24752
	v_cvt_pk_bf16_f32 v0, v96, v97
	v_cvt_pk_bf16_f32 v1, v98, v99
	ds_write_b16 v149, v0 offset:26112
	ds_write_b16_d16_hi v149, v0 offset:26384
	ds_write_b16 v149, v1 offset:26656
	ds_write_b16_d16_hi v149, v1 offset:26928
	v_cvt_pk_bf16_f32 v0, v100, v101
	v_cvt_pk_bf16_f32 v1, v102, v103
	ds_write_b16 v149, v0 offset:28288
	ds_write_b16_d16_hi v149, v0 offset:28560
	ds_write_b16 v149, v1 offset:28832
	ds_write_b16_d16_hi v149, v1 offset:29104
	v_cvt_pk_bf16_f32 v0, v104, v105
	v_cvt_pk_bf16_f32 v1, v106, v107
	ds_write_b16 v149, v0 offset:30464
	ds_write_b16_d16_hi v149, v0 offset:30736
	ds_write_b16 v149, v1 offset:31008
	ds_write_b16_d16_hi v149, v1 offset:31280
	v_cvt_pk_bf16_f32 v0, v108, v109
	v_cvt_pk_bf16_f32 v1, v110, v111
	ds_write_b16 v149, v0 offset:32640
	ds_write_b16_d16_hi v149, v0 offset:32912
	ds_write_b16 v149, v1 offset:33184
	ds_write_b16_d16_hi v149, v1 offset:33456
	s_waitcnt lgkmcnt(0)
	s_barrier
	s_setprio 0
	v_mov_b64_e32 v[250:251], v[206:207]
	s_waitcnt vmcnt(0)
	v_mov_b64_e32 v[210:211], 0x800
	v_mov_b64_e32 v[212:213], 0x7ff
	v_mov_b32_e32 v214, 0x3f317218
	v_mov_b64_e32 v[216:217], 0x700
	v_mov_b64_e32 v[218:219], 0x6ff
	v_mov_b32_e32 v240, 0x358637bd
	v_mov_b32_e32 v241, 1
	v_mov_b32_e32 v242, 0x41b17218
	v_mov_b32_e32 v243, 0x3600000
